# attention work queues: first NA/DIL unit of each wave assigned statically, the atomic queue only deals the leftovers (removes the 2048-wave dequeue burst)
# speedup vs baseline: 1.0126x; 1.0111x over previous
; #define LAS __attribute__((address_space(3)))
; DI void na_wave_unit(KArgs args, LAS unsigned char* L, const Ctx& c, int u, int lane, int wave) {
;     const int l = c.layer, head = u & 3, gr = u >> 2, rows = c.seqlen >> 6, seq = gr / rows, r = gr % rows;
;     int rs = r - 4; rs = rs < 0 ? 0 : (rs > rows - 8 ? rows - 8 : rs);
;     const bf16_t* PROJ = BIGP(bf16_t, B_PROJ);
;     const size_t tq0 = (size_t)seq * c.seqlen + (size_t)r * 64;
;     LAS bf16_t* Vt = (LAS bf16_t*)(L + wave * WAREA);
;     LAS float* BIAS = (LAS float*)(L + wave * WAREA + 9216);
;     const int rr = lane & 31, hh = lane >> 5;
; #pragma unroll
;     for (int w = 0; w < 4; ++w) { const int idx = w * 64 + lane, kw = idx >> 5, dc = idx & 31;
;         if (dc < 31) BIAS[idx] = args->in[3][(((size_t)l * 4 + head) * 15 + (rs + kw - r + 7)) * 31 + dc]; }
;     bf16x8 qf[2][4];
; #pragma unroll
;     for (int nt = 0; nt < 2; ++nt)
; #pragma unroll
;         for (int ks = 0; ks < 4; ++ks) qf[nt][ks] = *(const bf16x8*)(PROJ + (tq0 + 32 * nt + rr) * NPROJ + C_QA + 64 * head + 16 * ks + 8 * hh);
;     f32x16 o[2][2]; o[0][0] = zero16(); o[0][1] = zero16(); o[1][0] = zero16(); o[1][1] = zero16();
;     float m[2] = {-1e30f, -1e30f}, ls[2] = {0.f, 0.f};
;     for (int w = 0; w < 8; ++w) {
;         const size_t tk0 = (size_t)seq * c.seqlen + (size_t)(rs + w) * 64;
;         u32x4 vr[8]; bf16x8 kf[2][4];
;         load_v(vr, lane, [&](int key) { return PROJ + (tk0 + key) * NPROJ + C_VA + 64 * head; });
; #pragma unroll
;         for (int mt = 0; mt < 2; ++mt)
; #pragma unroll
;             for (int ks = 0; ks < 4; ++ks) kf[mt][ks] = *(const bf16x8*)(PROJ + (tk0 + 32 * mt + rr) * NPROJ + C_KA + 64 * head + 16 * ks + 8 * hh);
;         __builtin_amdgcn_sched_barrier(0);
;         asm volatile("s_waitcnt lgkmcnt(0)" ::: "memory");
;         put_vt(Vt, lane, vr);
;         f32x16 acc[2][2]; acc[0][0] = zero16(); acc[0][1] = zero16(); acc[1][0] = zero16(); acc[1][1] = zero16();
; #pragma unroll
;         for (int mt = 0; mt < 2; ++mt)
; #pragma unroll
;             for (int ks = 0; ks < 4; ++ks) { acc[mt][0] = MFMA32(kf[mt][ks], qf[0][ks], acc[mt][0]); acc[mt][1] = MFMA32(kf[mt][ks], qf[1][ks], acc[mt][1]); }
;         asm volatile("s_waitcnt lgkmcnt(0)" ::: "memory");
;         const LAS float* brow = BIAS + w * 32;
; #pragma unroll
.LBB0_651:
	v_writelane_b32 v254, s31, 33
	s_lshl_b32 s0, s28, 7
	v_readlane_b32 s1, v254, 14
	s_or_b32 s92, s0, s1
	s_lshr_b32 s91, s29, 4
	s_lshl_b64 s[0:1], s[92:93], 2
	s_waitcnt lgkmcnt(0)
	s_add_u32 s0, s72, s0
	s_addc_u32 s1, s73, s1
	s_add_u32 s0, s0, 0x20000
	s_addc_u32 s1, s1, 0
	v_writelane_b32 v254, s0, 34
	v_mov_b32_e32 v2, v177
	s_nop 0
	v_writelane_b32 v254, s1, 35
	v_writelane_b32 v254, s30, 36
	s_add_i32 s0, s30, -8
	v_writelane_b32 v254, s0, 37
	s_add_u32 s6, s72, 0x18200000
	v_readlane_b32 s0, v254, 23
	s_addc_u32 s7, s73, 0
	v_readlane_b32 s1, v254, 24
	s_and_b64 s[0:1], s[0:1], exec
	s_cselect_b32 s0, 12, 14
	v_writelane_b32 v254, s0, 39
	s_add_u32 s0, s72, 0x32600000
	v_writelane_b32 v254, s72, 40
	s_addc_u32 s1, s73, 0
	v_and_b32_e32 v5, 63, v2
	v_writelane_b32 v254, s73, 41
	v_writelane_b32 v254, s0, 42
	v_lshlrev_b32_e32 v6, 3, v2
	v_lshlrev_b32_e32 v7, 2, v5
	v_writelane_b32 v254, s1, 43
	v_readfirstlane_b32 s0, v2
	s_lshr_b32 s0, s0, 6
	s_mulk_i32 s0, 0x2800
	s_add_i32 s1, s0, 0
	v_or_b32_e32 v4, 64, v5
	v_and_b32_e32 v6, 56, v6
	v_bfe_u32 v182, v2, 3, 3
	v_mov_b32_e32 v10, s1
	v_add_u32_e32 v179, s1, v7
	v_lshrrev_b32_e32 v183, 5, v4
	v_or_b32_e32 v4, 0x80, v5
	v_and_b32_e32 v8, 24, v7
	v_mad_u32_u24 v11, v6, s27, v10
	v_bitop3_b32 v7, v182, v7, 24 bitop3:0x72
	v_cmp_eq_u32_e64 s[2:3], 0, v5
	v_lshrrev_b32_e32 v185, 5, v4
	v_or_b32_e32 v4, 0xc0, v5
	v_or_b32_e32 v9, v8, v182
	v_lshl_add_u32 v195, v7, 1, v11
	v_bitop3_b32 v7, v182, v8, 40 bitop3:0x36
	v_or_b32_e32 v5, 32, v5
	v_lshl_add_u32 v189, v9, 1, v11
	v_bitop3_b32 v9, v182, v8, 8 bitop3:0x36
	v_lshl_add_u32 v197, v7, 1, v11
	v_bitop3_b32 v7, v182, v8, 48 bitop3:0x36
	v_lshrrev_b32_e32 v14, 1, v5
	v_and_b32_e32 v176, 31, v2
	v_lshl_add_u32 v191, v9, 1, v11
	v_bitop3_b32 v9, v182, v8, 16 bitop3:0x36
	v_lshl_add_u32 v226, v7, 1, v11
	v_bitop3_b32 v7, v182, v8, 56 bitop3:0x36
	v_and_b32_e32 v8, 4, v182
	v_and_b32_e32 v15, 24, v14
	v_mad_u32_u24 v12, v176, s27, v10
	v_mad_u32_u24 v10, v5, s27, v10
	v_or_b32_e32 v16, v15, v8
	v_bfe_u32 v1, v2, 5, 1
	v_lshl_add_u32 v193, v9, 1, v11
	v_or_b32_e32 v9, 16, v8
	v_lshrrev_b32_e32 v2, 1, v2
	v_lshl_add_u32 v230, v16, 1, v10
	v_bitop3_b32 v16, v15, 8, v8 bitop3:0x36
	v_lshl_add_u32 v231, v16, 1, v10
	v_bitop3_b32 v16, v9, 8, v2 bitop3:0x34
	v_bitop3_b32 v9, v14, v9, 24 bitop3:0x6c
	v_lshl_add_u32 v233, v9, 1, v10
	v_xor_b32_e32 v9, 8, v9
	v_lshl_add_u32 v234, v9, 1, v10
	v_or_b32_e32 v9, 32, v8
	v_lshl_add_u32 v232, v16, 1, v12
	v_bitop3_b32 v16, v9, 8, v2 bitop3:0x34
	v_bitop3_b32 v9, v15, 8, v9 bitop3:0x36
	v_and_or_b32 v13, v2, 8, v8
	v_lshl_add_u32 v236, v9, 1, v10
	v_or_b32_e32 v9, 48, v8
	v_lshl_add_u32 v228, v13, 1, v12
	v_bitop3_b32 v13, v8, 8, v2 bitop3:0x34
	v_bitop3_b32 v2, v9, 8, v2 bitop3:0x34
	v_lshl_add_u32 v237, v2, 1, v12
	v_bitop3_b32 v2, v14, v9, 24 bitop3:0x6c
	v_lshl_add_u32 v227, v7, 1, v11
	v_lshlrev_b32_e32 v7, 2, v1
	v_lshl_add_u32 v238, v2, 1, v10
	v_xor_b32_e32 v2, 8, v2
	v_lshl_add_u32 v239, v2, 1, v10
	v_sub_u32_e64 v9, v176, 8 clamp
	v_or_b32_e32 v10, 1, v7
	v_writelane_b32 v254, s2, 44
	v_cmp_lt_u32_e64 s[18:19], v10, v9
	v_or_b32_e32 v10, 2, v7
	v_writelane_b32 v254, s3, 45
	v_cmp_ne_u32_e64 s[2:3], 31, v176
	v_cmp_lt_u32_e64 s[20:21], v10, v9
	v_or_b32_e32 v10, 3, v7
	v_writelane_b32 v254, s2, 46
	v_cmp_lt_u32_e64 s[22:23], v10, v9
	v_or_b32_e32 v10, 8, v7
	v_writelane_b32 v254, s3, 47
	v_cmp_lt_u32_e64 s[2:3], v10, v9
	v_or_b32_e32 v10, 9, v7
	v_cmp_lt_u32_e64 s[4:5], v10, v9
	v_or_b32_e32 v10, 10, v7
	v_max_u32_e32 v2, 8, v176
	v_cmp_lt_u32_e64 s[30:31], v10, v9
	v_or_b32_e32 v10, 11, v7
	v_add_u32_e32 v2, 8, v2
	v_cmp_lt_u32_e64 s[34:35], v10, v9
	v_or_b32_e32 v10, 16, v7
	v_cmp_ge_u32_e32 vcc, v10, v9
	v_cmp_lt_u32_e64 s[24:25], v10, v2
	v_or_b32_e32 v10, 17, v7
	s_and_b64 s[36:37], vcc, s[24:25]
	v_cmp_ge_u32_e32 vcc, v10, v9
	v_cmp_lt_u32_e64 s[26:27], v10, v2
	v_or_b32_e32 v10, 18, v7
	s_mov_b64 s[24:25], s[2:3]
	s_and_b64 s[2:3], vcc, s[26:27]
	v_cmp_ge_u32_e32 vcc, v10, v9
	v_cmp_lt_u32_e64 s[28:29], v10, v2
	v_or_b32_e32 v10, 19, v7
	v_lshl_add_u32 v229, v13, 1, v12
; #define LAS __attribute__((address_space(3)))
; DI int crow(int reg, int h) { return (reg & 3) + 8 * (reg >> 2) + 4 * h; }
; DI void na_wave_unit(KArgs args, LAS unsigned char* L, const Ctx& c, int u, int lane, int wave) {
;     ...
;         for (int nt = 0; nt < 2; ++nt) { const int qc = 32 * nt + rr; int ws = qc - 8; ws = ws < 0 ? 0 : (ws > 48 ? 48 : ws);
; #pragma unroll
;             for (int mt = 0; mt < 2; ++mt) {
;                 const volatile LAS float* bp = brow + (32 * mt + 4 * hh - qc + 15); float bv[16];
; #pragma unroll
;                 for (int g = 0; g < 16; ++g) { const bool live = (mt == nt) || (nt == 0 ? g < 4 : g >= 12);
;                     bv[g] = live ? bp[(g & 3) + 8 * (g >> 2)] : 0.f; }
; #pragma unroll
;                 for (int g = 0; g < 16; ++g) { const bool live = (mt == nt) || (nt == 0 ? g < 4 : g >= 12); const int kc = 32 * mt + crow(g, hh); const bool ok = live && (kc >= ws) && (kc < ws + 16);
;                     acc[mt][nt][g] = ok ? acc[mt][nt][g] * 0.125f + bv[g] : -1e30f; } } }
; DI void attn_wave_units(KArgs args, LAS unsigned char* L, const Ctx& c) {
;     int tid = c.tid; asm volatile("" : "+v"(tid)); const int lane = tid & 63, wave = __builtin_amdgcn_readfirstlane(tid >> 6);
;     const int nch_ = c.stok >> 6, N_NA = nch_ * 4, N_DIL = nch_ * 6;
;     unsigned* q = (unsigned*)(c.ws + WS_CTL) + 32768 + 128 * (c.layer * 4 + c.slab);
;     for (;;) { unsigned u = 0; if (lane == 0) u = __hip_atomic_fetch_add(q, 1u, __ATOMIC_RELAXED, __HIP_MEMORY_SCOPE_AGENT);
;         u = (unsigned)__builtin_amdgcn_readfirstlane((int)u); if (u >= (unsigned)N_NA) break; na_wave_unit(args, L, c, (int)u, lane, wave); }
	v_lshl_add_u32 v235, v16, 1, v12
	v_cmp_lt_u32_e64 s[16:17], v7, v9
	s_and_b64 s[38:39], vcc, s[28:29]
	s_mov_b64 s[28:29], s[30:31]
	v_cmp_ge_u32_e32 vcc, v10, v9
	v_cmp_lt_u32_e64 s[30:31], v10, v2
	v_or_b32_e32 v9, 24, v7
	v_or_b32_e32 v10, 25, v7
	v_or_b32_e32 v12, 26, v7
	v_or_b32_e32 v14, 27, v7
	v_or_b32_e32 v15, 32, v7
	v_or_b32_e32 v16, 33, v7
	v_or_b32_e32 v17, 34, v7
	v_or_b32_e32 v18, 35, v7
	v_cmp_lt_u32_e64 s[42:43], v9, v2
	v_cmp_lt_u32_e64 s[44:45], v10, v2
	v_cmp_lt_u32_e64 s[46:47], v12, v2
	v_cmp_lt_u32_e64 s[48:49], v14, v2
	v_cmp_lt_u32_e64 s[50:51], v15, v2
	v_cmp_lt_u32_e64 s[52:53], v16, v2
	v_cmp_lt_u32_e64 s[54:55], v17, v2
	v_cmp_lt_u32_e64 s[56:57], v18, v2
	v_min_u32_e32 v2, 56, v5
	v_add_u32_e32 v19, -8, v2
	v_add_u32_e32 v20, 8, v2
	v_or_b32_e32 v2, 40, v7
	s_and_b64 s[40:41], vcc, s[30:31]
	v_cmp_ge_u32_e32 vcc, v2, v19
	v_cmp_lt_u32_e64 s[66:67], v2, v20
	v_or_b32_e32 v2, 41, v7
	s_mov_b64 s[30:31], s[34:35]
	s_mov_b64 s[34:35], s[36:37]
	s_mov_b64 s[36:37], s[2:3]
	v_cmp_lt_u32_e64 s[2:3], v15, v19
	s_and_b64 s[76:77], vcc, s[66:67]
	v_cmp_ge_u32_e32 vcc, v2, v19
	v_cmp_lt_u32_e64 s[68:69], v2, v20
	v_or_b32_e32 v2, 42, v7
	v_cmp_lt_u32_e64 s[72:73], v17, v19
	s_mov_b64 s[66:67], s[2:3]
	s_and_b64 s[2:3], vcc, s[68:69]
	v_cmp_ge_u32_e32 vcc, v2, v19
	v_cmp_lt_u32_e64 s[70:71], v2, v20
	v_or_b32_e32 v2, 43, v7
	s_and_b64 s[78:79], vcc, s[70:71]
	s_mov_b64 s[70:71], s[72:73]
	v_cmp_ge_u32_e32 vcc, v2, v19
	v_cmp_lt_u32_e64 s[72:73], v2, v20
	v_or_b32_e32 v2, 48, v7
	v_cmp_lt_u32_e64 s[82:83], v2, v20
	v_or_b32_e32 v2, 49, v7
	v_cmp_lt_u32_e64 s[84:85], v2, v20
	v_lshlrev_b32_e32 v2, 4, v1
	v_mul_u32_u24_e32 v13, 0x90, v5
	v_lshl_add_u64 v[198:199], s[6:7], 0, v[2:3]
	v_or_b32_e32 v2, s0, v2
	v_lshlrev_b32_e32 v5, 2, v5
	v_sub_u32_e32 v5, v2, v5
	v_readlane_b32 s0, v253, 55
	s_mov_b64 s[26:27], s[4:5]
	v_cmp_lt_u32_e64 s[60:61], v10, v19
	v_add_u32_e32 v240, s0, v5
	v_lshlrev_b32_e32 v5, 2, v176
	v_cmp_lt_u32_e64 s[4:5], v16, v19
	v_lshl_add_u32 v10, v8, 1, s1
	v_lshlrev_b32_e32 v8, 1, v6
	v_or_b32_e32 v16, 56, v7
	v_sub_u32_e32 v2, v2, v5
	v_readlane_b32 s0, v253, 56
	v_cmp_lt_u32_e64 s[62:63], v12, v19
	v_add_u32_e32 v12, s1, v8
	v_add_u32_e32 v241, s0, v2
	v_cmp_lt_u32_e64 s[0:1], v16, v20
	v_or_b32_e32 v17, 57, v7
	v_cmp_lt_u32_e64 s[74:75], v18, v19
	v_writelane_b32 v254, s0, 48
	v_or_b32_e32 v18, 58, v7
	v_cmp_lt_u32_e64 s[64:65], v14, v19
	v_writelane_b32 v254, s1, 49
	v_cmp_lt_u32_e64 s[0:1], v17, v20
	v_or_b32_e32 v14, 50, v7
	v_or_b32_e32 v15, 51, v7
	v_writelane_b32 v254, s0, 50
	v_or_b32_e32 v7, 59, v7
	v_lshrrev_b32_e32 v187, 5, v4
	v_writelane_b32 v254, s1, 51
	v_cmp_lt_u32_e64 s[0:1], v18, v20
	v_lshlrev_b32_e32 v4, 3, v1
	v_mul_u32_u24_e32 v11, 0x90, v176
	v_writelane_b32 v254, s0, 52
	v_cmp_lt_u32_e64 s[58:59], v9, v19
	v_mul_u32_u24_e32 v19, 0x90, v182
	v_writelane_b32 v254, s1, 53
	v_cmp_lt_u32_e64 s[0:1], v7, v20
	v_mov_b32_e32 v9, v3
	v_or_b32_e32 v184, 8, v182
	v_writelane_b32 v254, s0, 54
	v_or_b32_e32 v186, 16, v182
	v_or_b32_e32 v188, 24, v182
	v_or_b32_e32 v190, 32, v182
	v_or_b32_e32 v192, 40, v182
	v_or_b32_e32 v194, 48, v182
	v_or_b32_e32 v196, 56, v182
	s_mov_b64 s[68:69], s[4:5]
	s_and_b64 s[80:81], vcc, s[72:73]
	s_mov_b64 s[72:73], s[74:75]
	s_mov_b64 s[74:75], s[76:77]
	s_mov_b64 s[76:77], s[2:3]
	v_lshl_add_u64 v[200:201], s[6:7], 0, v[8:9]
	v_lshlrev_b32_e32 v2, 1, v4
	v_add_u32_e32 v242, v10, v11
	v_add_u32_e32 v243, v10, v13
	v_add_u32_e32 v244, v12, v19
	v_lshlrev_b32_e32 v202, 1, v6
	v_cmp_lt_u32_e64 s[86:87], v14, v20
	v_cmp_lt_u32_e64 s[88:89], v15, v20
	v_writelane_b32 v254, s1, 55
	v_readfirstlane_b32 s0, v0
	s_nop 1
	s_lshr_b32 s0, s0, 6
	v_readlane_b32 s1, v253, 59
	s_nop 1
	s_lshl_b32 s2, s1, 3
	s_add_i32 s2, s2, s0
	v_readlane_b32 s4, v254, 23
	v_readlane_b32 s5, v254, 24
	s_nop 1
	s_and_b64 s[4:5], s[4:5], exec
	s_cselect_b32 s3, 0xc0, 24
	s_cmp_lt_u32 s1, s3
	s_cselect_b32 s3, 1, 0
	s_cmp_eq_u32 s0, 0
	s_cselect_b32 s0, s3, 0
	s_cmp_lg_u32 s0, 0
	s_cbranch_scc1 .LBB0_653
	s_cmp_ge_u32 s2, s91
	s_cbranch_scc1 .LBB0_653
	s_branch .Lna_body

; #define LAS __attribute__((address_space(3)))
; DI void na_wave_unit(KArgs args, LAS unsigned char* L, const Ctx& c, int u, int lane, int wave) {
;     const int l = c.layer, head = u & 3, gr = u >> 2, rows = c.seqlen >> 6, seq = gr / rows, r = gr % rows;
;     int rs = r - 4; rs = rs < 0 ? 0 : (rs > rows - 8 ? rows - 8 : rs);
;     const bf16_t* PROJ = BIGP(bf16_t, B_PROJ);
;     const size_t tq0 = (size_t)seq * c.seqlen + (size_t)r * 64;
;     LAS bf16_t* Vt = (LAS bf16_t*)(L + wave * WAREA);
;     LAS float* BIAS = (LAS float*)(L + wave * WAREA + 9216);
;     const int rr = lane & 31, hh = lane >> 5;
; #pragma unroll
;     for (int w = 0; w < 4; ++w) { const int idx = w * 64 + lane, kw = idx >> 5, dc = idx & 31;
;         if (dc < 31) BIAS[idx] = args->in[3][(((size_t)l * 4 + head) * 15 + (rs + kw - r + 7)) * 31 + dc]; }
; DI void attn_wave_units(KArgs args, LAS unsigned char* L, const Ctx& c) {
;     ...
;     for (;;) { unsigned u = 0; if (lane == 0) u = __hip_atomic_fetch_add(q, 1u, __ATOMIC_RELAXED, __HIP_MEMORY_SCOPE_AGENT);
;         u = (unsigned)__builtin_amdgcn_readfirstlane((int)u); if (u >= (unsigned)N_NA) break; na_wave_unit(args, L, c, (int)u, lane, wave); }
.LBB0_657:
	s_or_b64 exec, exec, s[2:3]
	v_readfirstlane_b32 s2, v4
	v_readlane_b32 s0, v254, 23
	v_readlane_b32 s1, v254, 24
	s_nop 1
	s_and_b64 s[0:1], s[0:1], exec
	s_cselect_b32 s3, 0xc0, 24
	s_cselect_b32 s4, 0, 0x80
	v_readlane_b32 s5, v254, 2
	s_nop 1
	s_lshl_b32 s5, s5, 3
	s_sub_u32 s0, s91, s5
	s_cselect_b32 s0, 0, s0
	s_add_i32 s0, s0, s3
	s_add_i32 s0, s0, s4
	s_cmp_ge_u32 s2, s0
	s_mov_b64 s[0:1], -1
	s_cbranch_scc1 .LBB0_652
	s_cmp_lt_u32 s2, s3
	s_cbranch_scc1 .Lna_map_scan
	s_sub_i32 s2, s2, s3
	s_cmp_lt_u32 s2, s4
	s_cbranch_scc1 .Lna_map_sel
	s_sub_i32 s2, s2, s4
	s_add_i32 s2, s2, s5
	s_branch .Lna_body
.Lna_map_sel:
	s_add_i32 s2, s2, 0xc0
	s_branch .Lna_body
.Lna_map_scan:
	s_lshl_b32 s2, s2, 3
.Lna_body:
	s_lshr_b32 s0, s2, 2
	v_readlane_b32 s1, v254, 33
	s_and_b32 s92, s0, s1
	v_sub_co_u32_e64 v4, s[4:5], s92, 4
	s_and_b32 s3, s2, 3
	v_readfirstlane_b32 s1, v4
	v_readlane_b32 s2, v254, 37
	s_min_i32 s1, s1, s2
	s_and_b64 s[4:5], s[4:5], exec
	s_cselect_b32 s2, 0, s1
	s_mov_b64 s[94:95], exec
	v_readlane_b32 s4, v254, 46
	v_readlane_b32 s5, v254, 47
	s_and_b64 s[4:5], s[94:95], s[4:5]
	s_mov_b64 exec, s[4:5]
	s_cbranch_execz .LBB0_660
	s_sub_i32 s1, s2, s92
	s_mov_b32 s5, s93
	s_mov_b64 s[8:9], s[92:93]
	s_mov_b64 s[92:93], s[6:7]
	v_readlane_b32 s6, v254, 30
	v_readlane_b32 s7, v254, 31
	s_load_dwordx2 vcc, s[6:7], 0x18
	s_add_i32 s1, s1, 7
	v_readlane_b32 s4, v254, 15
	s_or_b32 s4, s3, s4
	v_add_u32_e32 v4, s1, v1
	s_mul_i32 s4, s4, 15
	s_mov_b32 s33, s91
	s_mov_b64 s[90:91], s[88:89]
	s_mov_b64 s[88:89], s[86:87]
	s_mov_b64 s[86:87], s[84:85]
	s_mov_b64 s[84:85], s[82:83]
	s_mov_b64 s[82:83], s[80:81]
	s_mov_b64 s[80:81], s[78:79]
	s_mov_b64 s[78:79], s[76:77]
	s_mov_b64 s[76:77], s[74:75]
	s_mov_b64 s[74:75], s[72:73]
	s_mov_b64 s[72:73], s[70:71]
	s_mov_b64 s[70:71], s[68:69]
	s_mov_b64 s[68:69], s[66:67]
	s_mov_b64 s[66:67], s[64:65]
	s_mov_b64 s[64:65], s[62:63]
	s_mov_b64 s[62:63], s[60:61]
	s_mov_b64 s[60:61], s[58:59]
	s_mov_b64 s[58:59], s[56:57]
	s_mov_b64 s[56:57], s[54:55]
	s_mov_b64 s[54:55], s[52:53]
	s_mov_b64 s[52:53], s[50:51]
	s_mov_b64 s[50:51], s[48:49]
	s_mov_b64 s[48:49], s[46:47]
	s_mov_b64 s[46:47], s[44:45]
	s_mov_b64 s[44:45], s[42:43]
	s_mov_b64 s[42:43], s[40:41]
	s_mov_b64 s[40:41], s[38:39]
	s_mov_b64 s[38:39], s[36:37]
	s_mov_b64 s[36:37], s[34:35]
	s_mov_b64 s[34:35], s[30:31]
	s_mov_b64 s[30:31], s[28:29]
	s_mov_b64 s[28:29], s[26:27]
	s_mov_b64 s[26:27], s[24:25]
	s_mov_b64 s[24:25], s[22:23]
	s_mov_b64 s[22:23], s[20:21]
	v_ashrrev_i32_e32 v5, 31, v4
	s_mov_b64 s[20:21], s[22:23]
	s_mov_b64 s[22:23], s[24:25]
	s_mov_b64 s[24:25], s[26:27]
	s_mov_b64 s[26:27], s[28:29]
	s_mov_b64 s[28:29], s[30:31]
	s_mov_b64 s[30:31], s[34:35]
	s_mov_b64 s[34:35], s[36:37]
	s_mov_b64 s[36:37], s[38:39]
	s_mov_b64 s[38:39], s[40:41]
	s_mov_b64 s[40:41], s[42:43]
	s_mov_b64 s[42:43], s[44:45]
	s_mov_b64 s[44:45], s[46:47]
	s_mov_b64 s[46:47], s[48:49]
	s_mov_b64 s[48:49], s[50:51]
	s_mov_b64 s[50:51], s[52:53]
	s_mov_b64 s[52:53], s[54:55]
	s_mov_b64 s[54:55], s[56:57]
	s_mov_b64 s[56:57], s[58:59]
	s_mov_b64 s[58:59], s[60:61]
	s_mov_b64 s[60:61], s[62:63]
	s_mov_b64 s[62:63], s[64:65]
	s_mov_b64 s[64:65], s[66:67]
	s_mov_b64 s[66:67], s[68:69]
	s_mov_b64 s[68:69], s[70:71]
	s_mov_b64 s[70:71], s[72:73]
	s_mov_b64 s[72:73], s[74:75]
	s_mov_b64 s[74:75], s[76:77]
	s_mov_b64 s[76:77], s[78:79]
	s_mov_b64 s[78:79], s[80:81]
	s_mov_b64 s[80:81], s[82:83]
	s_mov_b64 s[82:83], s[84:85]
	s_mov_b64 s[84:85], s[86:87]
	s_mov_b64 s[86:87], s[88:89]
	s_mov_b64 s[88:89], s[90:91]
	s_mov_b32 s91, s33
	v_lshl_add_u64 v[4:5], v[4:5], 0, s[4:5]
	s_waitcnt lgkmcnt(0)
	v_mov_b64_e32 v[6:7], vcc
	s_movk_i32 s33, 0x7c
	v_mad_u64_u32 v[8:9], vcc, v4, s33, v[6:7]
	v_mad_i32_i24 v9, v5, s33, v9
	v_lshlrev_b32_e32 v4, 2, v176
	v_mov_b32_e32 v5, v3
	v_lshl_add_u64 v[8:9], v[8:9], 0, v[4:5]
	global_load_dword v12, v[8:9], off
	v_add_u32_e32 v8, s1, v183
	v_ashrrev_i32_e32 v9, 31, v8
	v_lshl_add_u64 v[8:9], v[8:9], 0, s[4:5]
	v_mad_u64_u32 v[10:11], vcc, v8, s33, v[6:7]
	v_mad_i32_i24 v11, v9, s33, v11
	v_lshl_add_u64 v[8:9], v[10:11], 0, v[4:5]
	global_load_dword v8, v[8:9], off
	s_mov_b64 s[6:7], s[92:93]
	s_mov_b64 s[92:93], s[8:9]
	s_movk_i32 s90, 0x1c00
	s_waitcnt vmcnt(0)
	ds_write2st64_b32 v179, v12, v8 offset0:36 offset1:37
	v_add_u32_e32 v8, s1, v185
	v_ashrrev_i32_e32 v9, 31, v8
	v_lshl_add_u64 v[8:9], v[8:9], 0, s[4:5]
	v_mad_u64_u32 v[10:11], vcc, v8, s33, v[6:7]
	v_mad_i32_i24 v11, v9, s33, v11
	v_lshl_add_u64 v[8:9], v[10:11], 0, v[4:5]
	global_load_dword v10, v[8:9], off
	v_add_u32_e32 v8, s1, v187
	v_ashrrev_i32_e32 v9, 31, v8
	v_lshl_add_u64 v[8:9], v[8:9], 0, s[4:5]
	v_mad_u64_u32 v[6:7], s[4:5], v8, s33, v[6:7]
	v_mad_i32_i24 v7, v9, s33, v7
	v_lshl_add_u64 v[4:5], v[6:7], 0, v[4:5]
	global_load_dword v4, v[4:5], off
	s_waitcnt vmcnt(0)
	ds_write2st64_b32 v179, v10, v4 offset0:38 offset1:39

; DI void dil_wave_unit(KArgs args, LAS unsigned char* L, const Ctx& c, int u, int lane, int wave) {
;     const int hd = u & 1, uu = u >> 1, upg = c.stok >> 6, g = uu / upg, v = uu % upg, ups = c.seqlen >> 6, seq = v / ups, wq = v % ups;
;     const int dsh = 2 * g, dd = 1 << dsh, nb = ups >> dsh, cls = wq / nb, jb = wq % nb, head = 2 * g + hd;
;     const bf16_t* PROJ = BIGP(bf16_t, B_PROJ); const float* CS = WSP(float, WS_CS);
;     const size_t sb = (size_t)seq * c.seqlen;
;     const int rr = lane & 31, hh = lane >> 5;
;     LAS bf16_t* Vt = (LAS bf16_t*)(L + wave * WAREA);
;     bf16x8 qf[2][4];
; #pragma unroll
;     for (int nt = 0; nt < 2; ++nt) { const int pos = cls + dd * (64 * jb + 32 * nt + rr);
; #pragma unroll
;         for (int ks = 0; ks < 4; ++ks) qf[nt][ks] = *(const bf16x8*)(PROJ + (sb + pos) * NPROJ + C_QD + 64 * head + 16 * ks + 8 * hh);
;         RopeCS tq; rope_load(tq, CS + (size_t)pos * 64, hh); __builtin_amdgcn_sched_barrier(0);
;         rope_frag4(qf[nt], tq); }
;     f32x16 o[2][2]; o[0][0] = zero16(); o[0][1] = zero16(); o[1][0] = zero16(); o[1][1] = zero16();
;     float m[2] = {-1e30f, -1e30f}, ls[2] = {0.f, 0.f};
;     for (int kt = 0; kt < 3; ++kt) { const int kj = jb - 1 + kt;
;         if (kj < 0 || kj >= nb) continue;
;         u32x4 vr[8]; bf16x8 kfa[2][4];
;         load_v(vr, lane, [&](int key) { return PROJ + (sb + cls + (size_t)dd * (64 * kj + key)) * NPROJ + C_VD + 64 * head; });
; #pragma unroll
;         for (int mt = 0; mt < 2; ++mt) { const int pos = cls + dd * (64 * kj + 32 * mt + rr);
; #pragma unroll
;             for (int ks = 0; ks < 4; ++ks) kfa[mt][ks] = *(const bf16x8*)(PROJ + (sb + pos) * NPROJ + C_KD + 64 * head + 16 * ks + 8 * hh); }
;         __builtin_amdgcn_sched_barrier(0);
;         asm volatile("s_waitcnt lgkmcnt(0)" ::: "memory");
;         put_vt(Vt, lane, vr);
;         f32x16 acc[2][2]; acc[0][0] = zero16(); acc[0][1] = zero16(); acc[1][0] = zero16(); acc[1][1] = zero16();
; #pragma unroll
;         for (int mt = 0; mt < 2; ++mt) {
;             RopeCS tk; rope_load(tk, CS + (size_t)(cls + dd * (64 * kj + 32 * mt + rr)) * 64, hh); __builtin_amdgcn_sched_barrier(0);
;             rope_frag4(kfa[mt], tk);
; #pragma unroll
;             for (int ks = 0; ks < 4; ++ks) { acc[mt][0] = MFMA32(kfa[mt][ks], qf[0][ks], acc[mt][0]); acc[mt][1] = MFMA32(kfa[mt][ks], qf[1][ks], acc[mt][1]); } }
.LBB0_663:
	v_readlane_b32 s0, v254, 29
	v_readlane_b32 s4, v254, 23
	s_lshr_b32 s0, s0, 6
	v_readlane_b32 s5, v254, 24
	s_and_b64 s[2:3], s[4:5], exec
	v_readlane_b32 s8, v254, 40
	s_cselect_b32 s62, 0xc00, s33
	v_readlane_b32 s9, v254, 41
	s_add_u32 s2, s8, 0x35e00000
	s_addc_u32 s3, s9, 0
	v_writelane_b32 v254, s2, 60
	s_add_u32 s1, s8, 0x37600000
	s_mov_b32 s58, 0xf000
	v_writelane_b32 v254, s3, 61
	v_writelane_b32 v254, s1, 62
	s_addc_u32 s1, s9, 0
	v_writelane_b32 v254, s1, 63
	v_readfirstlane_b32 s1, v177
	v_and_b32_e32 v1, 63, v177
	s_lshr_b32 s1, s1, 6
	v_cmp_eq_u32_e64 s[2:3], 0, v1
	s_mulk_i32 s1, 0x2800
	s_add_i32 s1, s1, 0
	v_writelane_b32 v255, s2, 0
	v_lshlrev_b32_e32 v2, 3, v177
	v_and_b32_e32 v4, 56, v2
	v_writelane_b32 v255, s3, 1
	v_bfe_u32 v202, v177, 3, 3
	v_lshlrev_b32_e32 v2, 2, v177
	v_mov_b32_e32 v9, s1
	s_movk_i32 s2, 0x90
	v_and_b32_e32 v7, 24, v2
	v_mad_u32_u24 v10, v4, s2, v9
	v_bitop3_b32 v2, v202, v2, 24 bitop3:0x72
	v_or_b32_e32 v8, v7, v202
	v_lshl_add_u32 v231, v2, 1, v10
	v_bitop3_b32 v2, v202, v7, 40 bitop3:0x36
	v_lshl_add_u32 v228, v8, 1, v10
	v_bitop3_b32 v8, v202, v7, 8 bitop3:0x36
	v_lshl_add_u32 v232, v2, 1, v10
	v_bitop3_b32 v2, v202, v7, 48 bitop3:0x36
	v_and_b32_e32 v179, 31, v177
	v_lshl_add_u32 v229, v8, 1, v10
	v_bitop3_b32 v8, v202, v7, 16 bitop3:0x36
	v_lshl_add_u32 v233, v2, 1, v10
	v_bitop3_b32 v2, v202, v7, 56 bitop3:0x36
	v_and_b32_e32 v7, 4, v202
	v_lshrrev_b32_e32 v11, 1, v177
	v_lshl_add_u32 v230, v8, 1, v10
	v_lshl_add_u32 v234, v2, 1, v10
	v_mad_u32_u24 v10, v179, s2, v9
	v_and_or_b32 v13, v11, 8, v7
	v_lshl_add_u32 v235, v13, 1, v10
	v_bitop3_b32 v13, v7, 8, v11 bitop3:0x34
	v_lshl_add_u32 v236, v13, 1, v10
	v_or_b32_e32 v13, 32, v1
	v_lshrrev_b32_e32 v15, 1, v13
	v_and_b32_e32 v16, 24, v15
	v_mad_u32_u24 v9, v13, s2, v9
	v_or_b32_e32 v17, v16, v7
	v_or_b32_e32 v8, 16, v7
	v_lshl_add_u32 v237, v17, 1, v9
	v_bitop3_b32 v17, v16, 8, v7 bitop3:0x36
	v_lshl_add_u32 v238, v17, 1, v9
	v_bitop3_b32 v17, v8, 8, v11 bitop3:0x34
	v_bitop3_b32 v8, v15, v8, 24 bitop3:0x6c
	v_lshl_add_u32 v240, v8, 1, v9
	v_xor_b32_e32 v8, 8, v8
	v_bfe_u32 v5, v177, 5, 1
	v_lshl_add_u32 v241, v8, 1, v9
	v_or_b32_e32 v8, 32, v7
	v_lshlrev_b32_e32 v2, 2, v5
	v_lshl_add_u32 v239, v17, 1, v10
	v_bitop3_b32 v17, v8, 8, v11 bitop3:0x34
	v_bitop3_b32 v8, v16, 8, v8 bitop3:0x36
	v_lshl_add_u32 v243, v8, 1, v9
	v_or_b32_e32 v8, 48, v7
	v_cmp_ge_u32_e64 s[2:3], v2, v179
	v_bitop3_b32 v11, v8, 8, v11 bitop3:0x34
	v_bitop3_b32 v8, v15, v8, 24 bitop3:0x6c
	v_writelane_b32 v254, s2, 44
	v_lshl_add_u32 v245, v8, 1, v9
	v_xor_b32_e32 v8, 8, v8
	v_writelane_b32 v254, s3, 45
	v_cmp_le_u32_e64 s[2:3], v2, v179
	v_lshl_add_u32 v246, v8, 1, v9
	v_or_b32_e32 v8, 1, v2
	v_writelane_b32 v254, s2, 58
	v_lshl_add_u32 v242, v17, 1, v10
	v_lshl_add_u32 v244, v11, 1, v10
	v_writelane_b32 v254, s3, 59
	v_cmp_ge_u32_e64 s[2:3], v8, v179
	v_or_b32_e32 v8, 2, v2
	v_or_b32_e32 v9, 33, v2
	v_writelane_b32 v254, s2, 56
	v_or_b32_e32 v10, 34, v2
	v_or_b32_e32 v15, 35, v2
	v_writelane_b32 v254, s3, 57
	v_cmp_lt_u32_e64 s[2:3], v2, v179
	v_or_b32_e32 v16, 40, v2
	v_or_b32_e32 v17, 41, v2
	v_writelane_b32 v254, s2, 48
	v_or_b32_e32 v18, 42, v2
	v_or_b32_e32 v19, 43, v2
	v_writelane_b32 v254, s3, 49
	v_cmp_ge_u32_e64 s[2:3], v8, v179
	v_or_b32_e32 v20, 48, v2
	v_or_b32_e32 v21, 49, v2
	v_writelane_b32 v254, s2, 46
	v_or_b32_e32 v22, 50, v2
	v_or_b32_e32 v23, 51, v2
	v_writelane_b32 v254, s3, 47
	v_cmp_le_u32_e64 s[2:3], v8, v179
	v_or_b32_e32 v8, 3, v2
	v_or_b32_e32 v24, 56, v2
	v_writelane_b32 v254, s2, 50
	v_or_b32_e32 v25, 57, v2
	v_or_b32_e32 v26, 58, v2
	v_writelane_b32 v254, s3, 51
	v_cmp_ge_u32_e64 s[2:3], v8, v179
	v_or_b32_e32 v27, 59, v2
	v_cmp_ge_u32_e64 s[86:87], v10, v13
	v_writelane_b32 v254, s2, 42
	v_cmp_le_u32_e64 s[88:89], v10, v13
	v_lshl_add_u32 v7, v7, 1, s1
	v_writelane_b32 v254, s3, 43
	v_cmp_le_u32_e64 s[2:3], v8, v179
	v_or_b32_e32 v8, 8, v2
	v_cmp_gt_u32_e64 s[54:55], 32, v1
	v_writelane_b32 v254, s2, 52
	v_lshlrev_b32_e32 v6, 3, v5
	v_mul_u32_u24_e32 v12, 0x90, v179
	v_writelane_b32 v254, s3, 53
	v_cmp_ge_u32_e64 s[2:3], v8, v179
	v_mul_u32_u24_e32 v14, 0x90, v13
	v_cmp_ge_u32_e64 s[82:83], v9, v13
	v_writelane_b32 v254, s2, 37
	v_cmp_le_u32_e64 s[84:85], v9, v13
	v_mul_u32_u24_e32 v29, 0x90, v202
	v_writelane_b32 v254, s3, 38
	v_cmp_le_u32_e64 s[2:3], v8, v179
	v_or_b32_e32 v8, 9, v2
	v_mov_b32_e32 v9, v3
	v_writelane_b32 v254, s2, 54
	v_or_b32_e32 v203, 8, v202
	v_or_b32_e32 v178, 16, v202
	v_writelane_b32 v254, s3, 55
	v_cmp_ge_u32_e64 s[2:3], v8, v179
; DI int crow(int reg, int h) { return (reg & 3) + 8 * (reg >> 2) + 4 * h; }
; DI void dil_wave_unit(KArgs args, LAS unsigned char* L, const Ctx& c, int u, int lane, int wave) {
;     ...
;         for (int nt = 0; nt < 2; ++nt) { const int qc = 32 * nt + rr;
; #pragma unroll
;             for (int mt = 0; mt < 2; ++mt)
; #pragma unroll
;                 for (int gg = 0; gg < 16; ++gg) { const int kc = 32 * mt + crow(gg, hh); const bool ok = (kt == 1) || (kt == 0 ? (kc >= qc) : (kc <= qc));
;                     acc[mt][nt][gg] = ok ? acc[mt][nt][gg] * 0.125f : -1e30f; } }
; DI void attn_wave_units(KArgs args, LAS unsigned char* L, const Ctx& c) {
;     ...
;     int tid2 = c.tid; asm volatile("" : "+v"(tid2)); const int lane2 = tid2 & 63, wave2 = __builtin_amdgcn_readfirstlane(tid2 >> 6);
;     for (;;) { unsigned u = 0; if (lane2 == 0) u = __hip_atomic_fetch_add(q + 64, 1u, __ATOMIC_RELAXED, __HIP_MEMORY_SCOPE_AGENT);
;         u = (unsigned)__builtin_amdgcn_readfirstlane((int)u); if (u >= (unsigned)N_DIL) break; dil_wave_unit(args, L, c, (int)u, lane2, wave2); }
	v_or_b32_e32 v180, 24, v202
	v_or_b32_e32 v181, 32, v202
	v_writelane_b32 v254, s2, 30
	v_or_b32_e32 v251, 40, v202
	v_or_b32_e32 v226, 48, v202
	v_writelane_b32 v254, s3, 31
	v_cmp_le_u32_e64 s[2:3], v8, v179
	v_or_b32_e32 v8, 10, v2
	v_or_b32_e32 v227, 56, v202
	v_writelane_b32 v255, s2, 2
	v_lshlrev_b32_e32 v188, 1, v6
	v_add_u32_e32 v247, v7, v12
	v_writelane_b32 v255, s3, 3
	v_cmp_ge_u32_e64 s[2:3], v8, v179
	v_add_u32_e32 v248, v7, v14
	v_lshlrev_b32_e32 v190, 1, v4
	v_writelane_b32 v255, s2, 4
	v_cmp_ge_u32_e64 s[94:95], v17, v13
	v_cmp_le_u32_e64 s[10:11], v17, v13
	v_writelane_b32 v255, s3, 5
	v_cmp_le_u32_e64 s[2:3], v8, v179
	v_or_b32_e32 v8, 11, v2
	v_cmp_ge_u32_e64 s[12:13], v18, v13
	v_writelane_b32 v255, s2, 6
	v_cmp_le_u32_e64 s[14:15], v18, v13
	v_cmp_ge_u32_e64 s[16:17], v19, v13
	v_writelane_b32 v255, s3, 7
	v_cmp_ge_u32_e64 s[2:3], v8, v179
	v_cmp_le_u32_e64 s[18:19], v19, v13
	v_cmp_ge_u32_e64 s[20:21], v20, v13
	v_writelane_b32 v255, s2, 8
	v_cmp_le_u32_e64 s[22:23], v20, v13
	v_cmp_ge_u32_e64 s[24:25], v21, v13
	v_writelane_b32 v255, s3, 9
	v_cmp_le_u32_e64 s[2:3], v8, v179
	v_or_b32_e32 v8, 16, v2
	v_cmp_le_u32_e64 s[26:27], v21, v13
	v_writelane_b32 v255, s2, 10
	v_cmp_ge_u32_e64 s[28:29], v22, v13
	v_cmp_le_u32_e64 s[30:31], v22, v13
	v_writelane_b32 v255, s3, 11
	v_cmp_ge_u32_e64 s[2:3], v8, v179
	v_cmp_ge_u32_e64 s[34:35], v23, v13
	v_cmp_le_u32_e64 s[36:37], v23, v13
	v_writelane_b32 v255, s2, 12
	v_cmp_ge_u32_e64 s[38:39], v24, v13
	v_cmp_le_u32_e64 s[40:41], v24, v13
	v_writelane_b32 v255, s3, 13
	v_cmp_le_u32_e64 s[2:3], v8, v179
	v_or_b32_e32 v8, 17, v2
	v_cmp_ge_u32_e64 s[42:43], v25, v13
	v_writelane_b32 v255, s2, 14
	v_cmp_le_u32_e64 s[44:45], v25, v13
	v_cmp_ge_u32_e64 s[46:47], v26, v13
	v_writelane_b32 v255, s3, 15
	v_cmp_ge_u32_e64 s[2:3], v8, v179
	v_cmp_le_u32_e64 s[48:49], v26, v13
	v_cmp_ge_u32_e64 s[50:51], v27, v13
	v_writelane_b32 v255, s2, 16
	v_cmp_le_u32_e64 s[52:53], v27, v13
	s_nop 0
	v_writelane_b32 v255, s3, 17
	v_cmp_le_u32_e64 s[2:3], v8, v179
	v_or_b32_e32 v8, 18, v2
	s_nop 0
	v_writelane_b32 v255, s2, 18
	s_nop 1
	v_writelane_b32 v255, s3, 19
	v_cmp_ge_u32_e64 s[2:3], v8, v179
	s_nop 1
	v_writelane_b32 v255, s2, 20
	s_nop 1
	v_writelane_b32 v255, s3, 21
	v_cmp_le_u32_e64 s[2:3], v8, v179
	v_or_b32_e32 v8, 19, v2
	s_nop 0
	v_writelane_b32 v255, s2, 22
	s_nop 1
	v_writelane_b32 v255, s3, 23
	v_cmp_ge_u32_e64 s[2:3], v8, v179
	s_nop 1
	v_writelane_b32 v255, s2, 24
	s_nop 1
	v_writelane_b32 v255, s3, 25
	v_cmp_le_u32_e64 s[2:3], v8, v179
	v_or_b32_e32 v8, 24, v2
	s_nop 0
	v_writelane_b32 v255, s2, 26
	s_nop 1
	v_writelane_b32 v255, s3, 27
	v_cmp_ge_u32_e64 s[2:3], v8, v179
	s_nop 1
	v_writelane_b32 v255, s2, 28
	s_nop 1
	v_writelane_b32 v255, s3, 29
	v_cmp_le_u32_e64 s[2:3], v8, v179
	v_or_b32_e32 v8, 25, v2
	v_cmp_le_u32_e64 s[68:69], v8, v179
	v_writelane_b32 v255, s2, 30
	s_nop 1
	v_writelane_b32 v255, s3, 31
	v_cmp_ge_u32_e64 s[2:3], v8, v179
	v_or_b32_e32 v8, 26, v2
	v_cmp_ge_u32_e64 s[70:71], v8, v179
	v_cmp_le_u32_e64 s[72:73], v8, v179
	v_or_b32_e32 v8, 27, v2
	v_writelane_b32 v255, s2, 32
	v_cmp_ge_u32_e64 s[74:75], v8, v179
	v_cmp_le_u32_e64 s[76:77], v8, v179
	v_or_b32_e32 v8, 32, v2
	v_and_b32_e32 v2, 32, v177
	v_writelane_b32 v255, s3, 33
	v_lshl_add_u64 v[10:11], s[8:9], 0, v[2:3]
	s_mov_b64 s[2:3], 0x17e00000
	v_cmp_ge_u32_e64 s[78:79], v8, v13
	v_cmp_le_u32_e64 s[80:81], v8, v13
	v_lshlrev_b32_e32 v8, 1, v4
	v_lshl_add_u64 v[182:183], v[10:11], 0, s[2:3]
	s_and_b64 s[2:3], s[4:5], exec
	v_add_u32_e32 v28, s1, v8
	s_cselect_b32 s1, 9, 8
	v_writelane_b32 v255, s1, 34
	s_add_i32 s0, s0, -1
	v_writelane_b32 v255, s0, 35
	v_writelane_b32 v255, s54, 36
	v_lshlrev_b32_e32 v2, 4, v5
	v_lshl_add_u64 v[184:185], s[6:7], 0, v[8:9]
	v_writelane_b32 v255, s55, 37
	v_lshl_add_u64 v[186:187], s[6:7], 0, v[2:3]
	v_add_u32_e32 v249, v28, v29
	v_cmp_ge_u32_e64 s[8:9], v15, v13
	v_cmp_le_u32_e64 s[4:5], v15, v13
	v_cmp_ge_u32_e64 s[0:1], v16, v13
	v_cmp_le_u32_e64 s[2:3], v16, v13
	v_writelane_b32 v255, s62, 38
	v_readfirstlane_b32 s54, v0
	s_nop 1
	s_lshr_b32 s54, s54, 6
	v_readlane_b32 s55, v253, 59
	s_nop 1
	s_lshl_b32 s33, s55, 3
	s_add_i32 s33, s33, s54
	v_readlane_b32 s56, v254, 23
	v_readlane_b32 s57, v254, 24
	s_nop 1
	s_and_b64 s[56:57], s[56:57], exec
	s_cselect_b32 s59, 0xc0, 24
	s_cmp_lt_u32 s55, s59
	s_cselect_b32 s59, 1, 0
	s_cmp_eq_u32 s54, 0
	s_cselect_b32 s54, s59, 0
	s_cmp_lg_u32 s54, 0
	s_cbranch_scc1 .LBB0_666
	s_cmp_ge_u32 s33, s62
	s_cbranch_scc1 .LBB0_666
	s_branch .Ldil_body

; #define LAS __attribute__((address_space(3)))
; DI void dil_wave_unit(KArgs args, LAS unsigned char* L, const Ctx& c, int u, int lane, int wave) {
;     const int hd = u & 1, uu = u >> 1, upg = c.stok >> 6, g = uu / upg, v = uu % upg, ups = c.seqlen >> 6, seq = v / ups, wq = v % ups;
;     const int dsh = 2 * g, dd = 1 << dsh, nb = ups >> dsh, cls = wq / nb, jb = wq % nb, head = 2 * g + hd;
;     const bf16_t* PROJ = BIGP(bf16_t, B_PROJ); const float* CS = WSP(float, WS_CS);
;     const size_t sb = (size_t)seq * c.seqlen;
;     const int rr = lane & 31, hh = lane >> 5;
;     LAS bf16_t* Vt = (LAS bf16_t*)(L + wave * WAREA);
;     bf16x8 qf[2][4];
; #pragma unroll
;     for (int nt = 0; nt < 2; ++nt) { const int pos = cls + dd * (64 * jb + 32 * nt + rr);
; #pragma unroll
;         for (int ks = 0; ks < 4; ++ks) qf[nt][ks] = *(const bf16x8*)(PROJ + (sb + pos) * NPROJ + C_QD + 64 * head + 16 * ks + 8 * hh);
;         RopeCS tq; rope_load(tq, CS + (size_t)pos * 64, hh); __builtin_amdgcn_sched_barrier(0);
;         rope_frag4(qf[nt], tq); }
; DI void attn_wave_units(KArgs args, LAS unsigned char* L, const Ctx& c) {
;     ...
;     for (;;) { unsigned u = 0; if (lane2 == 0) u = __hip_atomic_fetch_add(q + 64, 1u, __ATOMIC_RELAXED, __HIP_MEMORY_SCOPE_AGENT);
;         u = (unsigned)__builtin_amdgcn_readfirstlane((int)u); if (u >= (unsigned)N_DIL) break; dil_wave_unit(args, L, c, (int)u, lane2, wave2); }
.LBB0_670:
	s_or_b64 exec, exec, s[54:55]
	v_readfirstlane_b32 s33, v2
	v_readlane_b32 s54, v254, 23
	v_readlane_b32 s55, v254, 24
	s_nop 1
	s_and_b64 s[54:55], s[54:55], exec
	s_cselect_b32 s56, 0xc0, 24
	s_cselect_b32 s57, 0, 0x80
	v_readlane_b32 s59, v254, 2
	s_nop 1
	s_lshl_b32 s59, s59, 3
	s_sub_u32 s54, s62, s59
	s_cselect_b32 s54, 0, s54
	s_add_i32 s54, s54, s56
	s_add_i32 s54, s54, s57
	s_cmp_ge_u32 s33, s54
	s_mov_b64 s[54:55], -1
	s_cbranch_scc1 .LBB0_665
	s_cmp_lt_u32 s33, s56
	s_cbranch_scc1 .Ldil_map_scan
	s_sub_i32 s33, s33, s56
	s_cmp_lt_u32 s33, s57
	s_cbranch_scc1 .Ldil_map_sel
	s_sub_i32 s33, s33, s57
	s_add_i32 s33, s33, s59
	s_branch .Ldil_body
.Ldil_map_sel:
	s_add_i32 s33, s33, 0xc0
	s_branch .Ldil_body
.Ldil_map_scan:
	s_lshl_b32 s33, s33, 3
.Ldil_body:
	s_and_b32 s58, s33, 1
	s_lshr_b32 s33, s33, 1
	v_readlane_b32 s54, v255, 34
	s_lshr_b32 s92, s33, s54
	v_readlane_b32 s54, v255, 35
	s_and_b32 s33, s33, s54
	v_readlane_b32 s57, v254, 32
	v_readlane_b32 s55, v254, 33
	s_lshr_b32 s54, s33, s57
	s_and_b32 s55, s33, s55
	s_lshl_b32 s33, s92, 1
	v_readlane_b32 s56, v254, 36
	s_lshr_b32 s63, s56, s33
	s_sub_i32 s56, s57, s33
	s_lshr_b32 s64, s55, s56
	s_add_i32 s56, s63, -1
	s_and_b32 s65, s55, s56
	s_lshl_b32 s62, s65, 6
	v_writelane_b32 v254, s58, 40
	v_or_b32_e32 v191, s62, v179
	s_mov_b32 s55, s93
	v_readlane_b32 s56, v254, 39
	v_lshlrev_b32_e32 v2, s33, v191
	s_lshl_b64 s[54:55], s[54:55], s56
	v_add_u32_e32 v2, s64, v2
	v_lshl_add_u64 v[6:7], s[54:55], 0, v[2:3]
	v_mov_b64_e32 v[4:5], s[6:7]
	s_or_b32 s58, s33, s58
	v_mad_u64_u32 v[8:9], s[56:57], v6, s90, v[4:5]
	v_mad_u32_u24 v9, v7, s90, v9
	s_lshl_b32 vcc_lo, s58, 7
	s_mov_b32 vcc_hi, s93
	v_lshl_add_u64 v[6:7], v[8:9], 0, vcc
	v_mov_b32_e32 v189, v3
	v_lshlrev_b64 v[22:23], 8, v[2:3]
	v_lshl_add_u64 v[18:19], v[6:7], 0, v[188:189]
	v_lshl_add_u64 v[50:51], v[182:183], 0, v[22:23]
	global_load_dwordx4 v[6:9], v[18:19], off offset:1536
	global_load_dwordx4 v[10:13], v[18:19], off offset:1568
	global_load_dwordx4 v[14:17], v[18:19], off offset:1600
	s_nop 0
	global_load_dwordx4 v[18:21], v[18:19], off offset:1632
	s_nop 0
	global_load_dwordx4 v[22:25], v[50:51], off offset:16
	global_load_dwordx4 v[26:29], v[50:51], off
	global_load_dwordx4 v[30:33], v[50:51], off offset:144
	global_load_dwordx4 v[34:37], v[50:51], off offset:128
	global_load_dwordx4 v[38:41], v[50:51], off offset:80
	global_load_dwordx4 v[42:45], v[50:51], off offset:64
	global_load_dwordx4 v[46:49], v[50:51], off offset:208
	s_nop 0
	global_load_dwordx4 v[50:53], v[50:51], off offset:192
	s_waitcnt vmcnt(0)
	v_lshlrev_b32_e32 v54, 16, v6
	v_and_b32_e32 v55, 0xffff0000, v6
	v_lshlrev_b32_e32 v56, 16, v14
	v_and_b32_e32 v57, 0xffff0000, v14
	v_pk_mul_f32 v[58:59], v[34:35], v[56:57]
	v_pk_mul_f32 v[34:35], v[34:35], v[54:55]
	v_pk_fma_f32 v[58:59], v[26:27], v[54:55], v[58:59] neg_lo:[0,0,1] neg_hi:[0,0,1]
	v_pk_fma_f32 v[26:27], v[26:27], v[56:57], v[34:35]
	v_lshlrev_b32_e32 v14, 16, v15
	v_and_b32_e32 v15, 0xffff0000, v15
	v_cvt_pk_bf16_f32 v150, v26, v27
	v_lshlrev_b32_e32 v6, 16, v7
	v_and_b32_e32 v7, 0xffff0000, v7
	v_pk_mul_f32 v[26:27], v[36:37], v[14:15]
	v_or_b32_e32 v2, 32, v191
	v_pk_fma_f32 v[26:27], v[28:29], v[6:7], v[26:27] neg_lo:[0,0,1] neg_hi:[0,0,1]
	v_pk_mul_f32 v[6:7], v[36:37], v[6:7]
	v_cvt_pk_bf16_f32 v147, v26, v27
	v_pk_fma_f32 v[6:7], v[28:29], v[14:15], v[6:7]
	v_lshlrev_b32_e32 v14, 16, v16
	v_and_b32_e32 v15, 0xffff0000, v16
	v_cvt_pk_bf16_f32 v151, v6, v7
	v_lshlrev_b32_e32 v6, 16, v8
	v_and_b32_e32 v7, 0xffff0000, v8
	v_pk_mul_f32 v[26:27], v[30:31], v[14:15]
	v_lshlrev_b32_e32 v8, 16, v17
	v_pk_fma_f32 v[26:27], v[22:23], v[6:7], v[26:27] neg_lo:[0,0,1] neg_hi:[0,0,1]
	v_pk_mul_f32 v[6:7], v[30:31], v[6:7]
	v_lshlrev_b32_e32 v2, s33, v2
	v_pk_fma_f32 v[6:7], v[22:23], v[14:15], v[6:7]
	v_add_u32_e32 v2, s64, v2
	v_cvt_pk_bf16_f32 v152, v6, v7
	v_lshlrev_b32_e32 v6, 16, v9
	v_and_b32_e32 v7, 0xffff0000, v9
	v_and_b32_e32 v9, 0xffff0000, v17
	v_pk_mul_f32 v[14:15], v[32:33], v[8:9]
	v_cvt_pk_bf16_f32 v148, v26, v27
	v_pk_fma_f32 v[14:15], v[24:25], v[6:7], v[14:15] neg_lo:[0,0,1] neg_hi:[0,0,1]
	v_pk_mul_f32 v[6:7], v[32:33], v[6:7]
	v_cvt_pk_bf16_f32 v149, v14, v15
	v_pk_fma_f32 v[6:7], v[24:25], v[8:9], v[6:7]
	v_lshlrev_b32_e32 v8, 16, v10
	v_and_b32_e32 v9, 0xffff0000, v10
	v_cvt_pk_bf16_f32 v153, v6, v7
	v_lshlrev_b32_e32 v6, 16, v18
	v_and_b32_e32 v7, 0xffff0000, v18
	v_pk_mul_f32 v[14:15], v[50:51], v[8:9]
	v_cvt_pk_bf16_f32 v146, v58, v59
	v_pk_fma_f32 v[14:15], v[42:43], v[6:7], v[14:15]
	v_pk_mul_f32 v[6:7], v[50:51], v[6:7]
	v_cvt_pk_bf16_f32 v154, v14, v15
	v_pk_fma_f32 v[6:7], v[42:43], v[8:9], v[6:7] neg_lo:[0,0,1] neg_hi:[0,0,1]
	v_lshlrev_b32_e32 v8, 16, v11
	v_and_b32_e32 v9, 0xffff0000, v11
	v_cvt_pk_bf16_f32 v158, v6, v7
	v_lshlrev_b32_e32 v6, 16, v19
	v_and_b32_e32 v7, 0xffff0000, v19
	v_pk_mul_f32 v[10:11], v[52:53], v[8:9]
	s_nop 0
	v_pk_fma_f32 v[10:11], v[44:45], v[6:7], v[10:11]
	v_pk_mul_f32 v[6:7], v[52:53], v[6:7]
	v_cvt_pk_bf16_f32 v155, v10, v11
	v_pk_fma_f32 v[6:7], v[44:45], v[8:9], v[6:7] neg_lo:[0,0,1] neg_hi:[0,0,1]
	v_lshlrev_b32_e32 v8, 16, v12
	v_and_b32_e32 v9, 0xffff0000, v12
	v_cvt_pk_bf16_f32 v159, v6, v7
	v_lshlrev_b32_e32 v6, 16, v20
	v_and_b32_e32 v7, 0xffff0000, v20
	v_pk_mul_f32 v[10:11], v[46:47], v[8:9]
	s_nop 0
	v_pk_fma_f32 v[10:11], v[38:39], v[6:7], v[10:11]
	v_pk_mul_f32 v[6:7], v[46:47], v[6:7]
	v_cvt_pk_bf16_f32 v156, v10, v11
	v_pk_fma_f32 v[6:7], v[38:39], v[8:9], v[6:7] neg_lo:[0,0,1] neg_hi:[0,0,1]
	v_lshlrev_b32_e32 v8, 16, v21
	v_and_b32_e32 v9, 0xffff0000, v21
	v_cvt_pk_bf16_f32 v160, v6, v7
	v_lshlrev_b32_e32 v6, 16, v13
	v_and_b32_e32 v7, 0xffff0000, v13
	v_pk_mul_f32 v[10:11], v[48:49], v[8:9]
	s_nop 0
	v_pk_fma_f32 v[10:11], v[40:41], v[6:7], v[10:11] neg_lo:[0,0,1] neg_hi:[0,0,1]
	v_pk_mul_f32 v[6:7], v[48:49], v[6:7]
	v_cvt_pk_bf16_f32 v161, v10, v11
	v_pk_fma_f32 v[6:7], v[40:41], v[8:9], v[6:7]
	s_nop 0
	v_cvt_pk_bf16_f32 v157, v6, v7
	v_lshl_add_u64 v[6:7], s[54:55], 0, v[2:3]
	v_mad_u64_u32 v[4:5], s[56:57], v6, s90, v[4:5]
	v_mad_u32_u24 v5, v7, s90, v5
	v_lshl_add_u64 v[4:5], v[4:5], 0, vcc
	v_lshl_add_u64 v[4:5], v[4:5], 0, v[188:189]
	global_load_dwordx4 v[40:43], v[4:5], off offset:1536
	global_load_dwordx4 v[16:19], v[4:5], off offset:1568
	global_load_dwordx4 v[36:39], v[4:5], off offset:1600
	global_load_dwordx4 v[12:15], v[4:5], off offset:1632
	v_lshlrev_b64 v[4:5], 8, v[2:3]
	v_lshl_add_u64 v[24:25], v[182:183], 0, v[4:5]
	global_load_dwordx4 v[28:31], v[24:25], off offset:16
	global_load_dwordx4 v[44:47], v[24:25], off
	global_load_dwordx4 v[32:35], v[24:25], off offset:144
	global_load_dwordx4 v[48:51], v[24:25], off offset:128
	global_load_dwordx4 v[4:7], v[24:25], off offset:80
	global_load_dwordx4 v[20:23], v[24:25], off offset:64
	global_load_dwordx4 v[8:11], v[24:25], off offset:208
	s_nop 0
	global_load_dwordx4 v[24:27], v[24:25], off offset:192
	s_waitcnt vmcnt(11)
; DI f32x16 zero16() { f32x16 z; for (int i = 0; i < 16; ++i) z[i] = 0.f; return z; }
; DI void dil_wave_unit(KArgs args, LAS unsigned char* L, const Ctx& c, int u, int lane, int wave) {
;     ...
;     for (int nt = 0; nt < 2; ++nt) { const int pos = cls + dd * (64 * jb + 32 * nt + rr);
; #pragma unroll
;         for (int ks = 0; ks < 4; ++ks) qf[nt][ks] = *(const bf16x8*)(PROJ + (sb + pos) * NPROJ + C_QD + 64 * head + 16 * ks + 8 * hh);
;         RopeCS tq; rope_load(tq, CS + (size_t)pos * 64, hh); __builtin_amdgcn_sched_barrier(0);
;         rope_frag4(qf[nt], tq); }
;     f32x16 o[2][2]; o[0][0] = zero16(); o[0][1] = zero16(); o[1][0] = zero16(); o[1][1] = zero16();
;     float m[2] = {-1e30f, -1e30f}, ls[2] = {0.f, 0.f};
	v_lshlrev_b32_e32 v52, 16, v40
	v_and_b32_e32 v53, 0xffff0000, v40
	s_waitcnt vmcnt(9)
	v_lshlrev_b32_e32 v54, 16, v36
	v_and_b32_e32 v55, 0xffff0000, v36
	s_waitcnt vmcnt(4)
	v_pk_mul_f32 v[56:57], v[48:49], v[54:55]
	v_pk_mul_f32 v[48:49], v[48:49], v[52:53]
	v_pk_fma_f32 v[56:57], v[44:45], v[52:53], v[56:57] neg_lo:[0,0,1] neg_hi:[0,0,1]
	v_pk_fma_f32 v[44:45], v[44:45], v[54:55], v[48:49]
	v_lshlrev_b32_e32 v36, 16, v37
	v_and_b32_e32 v37, 0xffff0000, v37
	v_cvt_pk_bf16_f32 v166, v44, v45
	v_lshlrev_b32_e32 v40, 16, v41
	v_and_b32_e32 v41, 0xffff0000, v41
	v_pk_mul_f32 v[44:45], v[50:51], v[36:37]
	s_add_i32 s65, s65, -1
	v_pk_fma_f32 v[44:45], v[46:47], v[40:41], v[44:45] neg_lo:[0,0,1] neg_hi:[0,0,1]
	v_pk_mul_f32 v[40:41], v[50:51], v[40:41]
	v_cvt_pk_bf16_f32 v163, v44, v45
	v_pk_fma_f32 v[36:37], v[46:47], v[36:37], v[40:41]
	v_lshlrev_b32_e32 v40, 16, v38
	v_cvt_pk_bf16_f32 v167, v36, v37
	v_lshlrev_b32_e32 v36, 16, v42
	v_and_b32_e32 v37, 0xffff0000, v42
	v_and_b32_e32 v41, 0xffff0000, v38
	v_pk_mul_f32 v[44:45], v[32:33], v[40:41]
	v_pk_mul_f32 v[32:33], v[32:33], v[36:37]
	v_pk_fma_f32 v[44:45], v[28:29], v[36:37], v[44:45] neg_lo:[0,0,1] neg_hi:[0,0,1]
	v_pk_fma_f32 v[28:29], v[28:29], v[40:41], v[32:33]
	v_lshlrev_b32_e32 v32, 16, v39
	v_and_b32_e32 v33, 0xffff0000, v39
	v_cvt_pk_bf16_f32 v168, v28, v29
	v_lshlrev_b32_e32 v28, 16, v43
	v_and_b32_e32 v29, 0xffff0000, v43
	v_pk_mul_f32 v[36:37], v[34:35], v[32:33]
	v_cvt_pk_bf16_f32 v162, v56, v57
	v_pk_fma_f32 v[36:37], v[30:31], v[28:29], v[36:37] neg_lo:[0,0,1] neg_hi:[0,0,1]
	v_pk_mul_f32 v[28:29], v[34:35], v[28:29]
	v_cvt_pk_bf16_f32 v164, v44, v45
	v_pk_fma_f32 v[28:29], v[30:31], v[32:33], v[28:29]
	v_lshlrev_b32_e32 v30, 16, v16
	v_cvt_pk_bf16_f32 v169, v28, v29
	v_lshlrev_b32_e32 v28, 16, v12
	v_and_b32_e32 v29, 0xffff0000, v12
	v_and_b32_e32 v31, 0xffff0000, v16
	s_waitcnt vmcnt(0)
	v_pk_mul_f32 v[32:33], v[24:25], v[30:31]
	v_pk_mul_f32 v[24:25], v[24:25], v[28:29]
	v_pk_fma_f32 v[32:33], v[20:21], v[28:29], v[32:33]
	v_pk_fma_f32 v[20:21], v[20:21], v[30:31], v[24:25] neg_lo:[0,0,1] neg_hi:[0,0,1]
	v_lshlrev_b32_e32 v16, 16, v17
	v_and_b32_e32 v17, 0xffff0000, v17
	v_cvt_pk_bf16_f32 v174, v20, v21
	v_lshlrev_b32_e32 v12, 16, v13
	v_and_b32_e32 v13, 0xffff0000, v13
	v_pk_mul_f32 v[20:21], v[26:27], v[16:17]
	v_cvt_pk_bf16_f32 v165, v36, v37
	v_pk_fma_f32 v[20:21], v[22:23], v[12:13], v[20:21]
	v_pk_mul_f32 v[12:13], v[26:27], v[12:13]
	v_cvt_pk_bf16_f32 v171, v20, v21
	v_pk_fma_f32 v[12:13], v[22:23], v[16:17], v[12:13] neg_lo:[0,0,1] neg_hi:[0,0,1]
	v_lshlrev_b32_e32 v16, 16, v18
	v_cvt_pk_bf16_f32 v175, v12, v13
	v_lshlrev_b32_e32 v12, 16, v14
	v_and_b32_e32 v13, 0xffff0000, v14
	v_and_b32_e32 v17, 0xffff0000, v18
	v_pk_mul_f32 v[20:21], v[8:9], v[16:17]
	v_pk_mul_f32 v[8:9], v[8:9], v[12:13]
	v_pk_fma_f32 v[20:21], v[4:5], v[12:13], v[20:21]
	v_pk_fma_f32 v[4:5], v[4:5], v[16:17], v[8:9] neg_lo:[0,0,1] neg_hi:[0,0,1]
	v_lshlrev_b32_e32 v8, 16, v15
	v_and_b32_e32 v9, 0xffff0000, v15
	v_cvt_pk_bf16_f32 v176, v4, v5
	v_lshlrev_b32_e32 v4, 16, v19
	v_and_b32_e32 v5, 0xffff0000, v19
	v_pk_mul_f32 v[12:13], v[10:11], v[8:9]
	v_mov_b32_e32 v16, v3
	v_pk_fma_f32 v[12:13], v[6:7], v[4:5], v[12:13] neg_lo:[0,0,1] neg_hi:[0,0,1]
	v_pk_mul_f32 v[4:5], v[10:11], v[4:5]
	v_mov_b32_e32 v17, v3
	v_pk_fma_f32 v[4:5], v[6:7], v[8:9], v[4:5]
	v_cvt_pk_bf16_f32 v170, v32, v33
	v_cvt_pk_bf16_f32 v172, v20, v21
	v_cvt_pk_bf16_f32 v177, v12, v13
	v_cvt_pk_bf16_f32 v173, v4, v5
	s_add_u32 s56, s54, s64
	v_mov_b32_e32 v2, v3
	v_mov_b32_e32 v4, v3
	v_mov_b32_e32 v5, v3
	v_mov_b32_e32 v6, v3
	v_mov_b32_e32 v7, v3
	v_mov_b32_e32 v8, v3
	v_mov_b32_e32 v9, v3
	v_mov_b32_e32 v10, v3
	v_mov_b32_e32 v11, v3
	v_mov_b32_e32 v12, v3
	v_mov_b32_e32 v13, v3
	v_mov_b32_e32 v14, v3
	v_mov_b32_e32 v15, v3
	v_mov_b32_e32 v199, 0
	v_mov_b32_e32 v198, 0xf149f2ca
	v_mov_b64_e32 v[32:33], v[16:17]
	v_mov_b64_e32 v[48:49], v[16:17]
	v_mov_b64_e32 v[64:65], v[16:17]
	v_mov_b64_e32 v[80:81], v[16:17]
	s_addc_u32 s57, s55, 0
	v_lshl_add_u64 v[194:195], v[184:185], 0, vcc
	v_lshl_add_u64 v[196:197], v[186:187], 0, vcc
	v_or_b32_e32 v192, s62, v202
	s_mov_b32 s66, 0
	s_mov_b32 s67, 0
	v_mov_b64_e32 v[30:31], v[14:15]
	v_mov_b64_e32 v[28:29], v[12:13]
	v_mov_b64_e32 v[26:27], v[10:11]
	v_mov_b64_e32 v[24:25], v[8:9]
	v_mov_b64_e32 v[22:23], v[6:7]
	v_mov_b64_e32 v[20:21], v[4:5]
	v_mov_b64_e32 v[18:19], v[2:3]
	v_mov_b64_e32 v[46:47], v[14:15]
	v_mov_b64_e32 v[44:45], v[12:13]
	v_mov_b64_e32 v[42:43], v[10:11]
	v_mov_b64_e32 v[40:41], v[8:9]
	v_mov_b64_e32 v[38:39], v[6:7]
	v_mov_b64_e32 v[36:37], v[4:5]
	v_mov_b64_e32 v[34:35], v[2:3]
	v_mov_b64_e32 v[62:63], v[14:15]
	v_mov_b64_e32 v[60:61], v[12:13]
	v_mov_b64_e32 v[58:59], v[10:11]
	v_mov_b64_e32 v[56:57], v[8:9]
	v_mov_b64_e32 v[54:55], v[6:7]
	v_mov_b64_e32 v[52:53], v[4:5]
	v_mov_b64_e32 v[50:51], v[2:3]
	v_mov_b64_e32 v[78:79], v[14:15]
	v_mov_b64_e32 v[76:77], v[12:13]
	v_mov_b64_e32 v[74:75], v[10:11]
	v_mov_b64_e32 v[72:73], v[8:9]
	v_mov_b64_e32 v[70:71], v[6:7]
	v_mov_b64_e32 v[68:69], v[4:5]
	v_mov_b64_e32 v[66:67], v[2:3]
	v_mov_b32_e32 v16, v198
	v_mov_b32_e32 v17, v199
	s_branch .LBB0_673
